# P5 order swap: PLE projection GEMM (P5b) before the output projection (P5a) so its stores drain under P5a's K-loop
# baseline (speedup 1.0000x reference)
.LBB0_931:
	s_or_b64 exec, exec, s[4:5]
	s_add_u32 s10, s50, 0x10000
	s_addc_u32 s11, s51, 0
	s_waitcnt vmcnt(15)
	v_cndmask_b32_e64 v1, 0, 1, s[70:71]
	s_add_u32 s12, s50, 0x14a00000
	v_cmp_ne_u32_e64 s[68:69], 1, v1
	s_addc_u32 s13, s51, 0
	v_mov_b32_e32 v188, 0x7f7f7f7f
	s_waitcnt lgkmcnt(0)
	v_mov_b32_e32 v0, 0x7f7f7f7f
	s_andn2_b64 vcc, exec, s[70:71]
	v_writelane_b32 v250, s68, 9
	s_barrier
	v_mbcnt_lo_u32_b32 v189, -1, 0
	v_mbcnt_hi_u32_b32 v189, -1, v189
	s_nop 0
	v_writelane_b32 v250, s69, 10
	s_mov_b64 s[100:101], s[74:75]
	s_branch .Lq5_B
.Lq5_A:
	s_mov_b64 s[74:75], s[100:101]
	v_mbcnt_lo_u32_b32 v189, -1, 0
	v_mbcnt_hi_u32_b32 v189, -1, v189
	s_and_b64 vcc, exec, s[68:69]
	s_cbranch_vccnz .LBB0_1004
	s_ashr_i32 s44, s2, 31
	s_lshr_b32 s6, s44, 29
	s_add_i32 s9, s2, s6
	s_and_b32 s6, s9, -8
	s_sub_i32 s14, s2, s6
	s_cmp_gt_i32 s14, -1
	s_cbranch_scc0 .LBB0_934
	s_lshl_b32 s8, s14, 5
	s_cbranch_execz .LBB0_935
	s_branch .LBB0_936

.LBB0_1003:
	s_waitcnt vmcnt(0)
	v_readlane_b32 s68, v250, 9
	s_mov_b32 s90, s42
	s_mov_b64 s[42:43], s[54:55]
	s_mov_b64 s[54:55], s[4:5]
	v_readlane_b32 s69, v250, 10
	s_barrier
	s_branch .Lq5_A
.LBB0_1004:
	s_and_b64 vcc, exec, s[42:43]
	s_mov_b64 s[8:9], 0
	s_cbranch_vccnz .LBB0_1006
	v_mbcnt_lo_u32_b32 v0, -1, 0
	v_mbcnt_hi_u32_b32 v0, -1, v0
	s_nop 0
	v_cmp_eq_u32_e32 vcc, 0, v0
	s_and_b64 s[8:9], vcc, exec
